# stack7 + s_nop pads removed from the prompt attention loops and tail (hazard tables re-derived, only required wait states kept)
# speedup vs baseline: 1.0129x; 1.0040x over previous
; #define WAIT_BAR(N) asm volatile("s_waitcnt vmcnt(" #N ") lgkmcnt(0)\n\ts_barrier":::"memory")
;   #define RESC() do{ if(resc){ asm volatile("s_waitcnt lgkmcnt(0)":::"memory"); \
;       _Pragma("unroll") for(int d_=0;d_<2;++d_) _Pragma("unroll") for(int r=0;r<16;++r)o[d_][r]*=wsf[crow(r,hi)]; } }while(0)
;   #define ROT() do{sl_prev=sl_cur;sl_cur=sl_next;sl_next=(sl_next==(NSLOT-1)*SLOTB)?0:sl_next+SLOTB;}while(0)
; template<int THRL> __device__ __forceinline__ void attn_unit(int b,int qb,const bf16*Q,const bf16*__restrict__ K,const bf16*__restrict__ V,bf16*O,char*shm,const float a2,const int t0,const float mref,bf16x8(&qr)[4],const bool pre,const bool hasnext,const int qbn,const bf16*Qn,const bf16*Kn,const int ...
;     ...
;   for(;t+5<NT;t+=2){
;     STEP(pB0,pB1,pA0,pA1,t,true,true,true);     WAIT_BAR(2); RESC(); ROT();
;     STEP(pA0,pA1,pB0,pB1,t+1,true,true,true);   WAIT_BAR(2); RESC(); ROT();
.LBB0_433:
	s_mov_b32 s29, s1
	v_add_f32_e32 v178, v198, v200
	v_add_f32_e32 v82, s61, v178
	v_add_f32_e32 v83, s80, v178
	v_add_f32_e32 v84, s81, v178
	v_add_f32_e32 v85, s82, v178
	v_add_f32_e32 v86, s83, v178
	v_add_f32_e32 v87, s84, v178
	v_add_f32_e32 v88, s85, v178
	v_add_f32_e32 v89, s86, v178
	v_add_f32_e32 v90, s87, v178
	v_add_f32_e32 v91, s88, v178
	v_add_f32_e32 v92, s89, v178
	v_add_f32_e32 v93, s90, v178
	v_add_f32_e32 v94, s91, v178
	v_add_f32_e32 v95, s97, v178
	v_add_f32_e32 v96, s62, v178
	v_add_f32_e32 v97, s63, v178
	v_add_u32_e32 v179, s3, v197
	ds_read_b64_tr_b16 v[162:163], v179 offset:24576
	ds_read_b64_tr_b16 v[164:165], v179 offset:25088
	v_add_f32_e32 v66, v50, v51
	v_add_f32_e32 v66, v52, v66
	v_add_f32_e32 v66, v53, v66
	v_add_f32_e32 v66, v54, v66
	v_add_f32_e32 v114, v55, v66
	v_cvt_pk_bf16_f32 v126, v50, v51
	v_cvt_pk_bf16_f32 v127, v52, v53
	v_add_f32_e32 v50, v176, v178
	v_add_f32_e32 v66, s61, v50
	v_add_f32_e32 v67, s80, v50
	v_add_f32_e32 v68, s81, v50
	v_add_f32_e32 v69, s82, v50
	v_add_f32_e32 v70, s83, v50
	v_add_f32_e32 v71, s84, v50
	v_add_f32_e32 v72, s85, v50
	v_add_f32_e32 v73, s86, v50
	v_add_f32_e32 v74, s87, v50
	v_add_f32_e32 v75, s88, v50
	v_add_f32_e32 v76, s89, v50
	v_add_f32_e32 v77, s90, v50
	v_add_f32_e32 v78, s91, v50
	v_add_f32_e32 v79, s97, v50
	v_add_f32_e32 v80, s62, v50
	v_add_f32_e32 v81, s63, v50
	s_waitcnt lgkmcnt(9)
	v_mfma_f32_32x32x16_bf16 v[82:97], v[158:161], v[98:101], v[82:97]
	ds_read_b64_tr_b16 v[158:159], v179 offset:28672
	ds_read_b64_tr_b16 v[160:161], v179 offset:29184
	v_add_f32_e32 v50, v56, v114
	v_add_f32_e32 v50, v57, v50
	v_add_f32_e32 v50, v58, v50
	v_add_f32_e32 v50, v59, v50
	v_cvt_pk_bf16_f32 v128, v54, v55
	v_cvt_pk_bf16_f32 v129, v56, v57
	s_waitcnt lgkmcnt(10)
	v_mfma_f32_32x32x16_bf16 v[66:81], v[154:157], v[98:101], v[66:81]
	ds_read_b64_tr_b16 v[154:155], v179 offset:25600
	ds_read_b64_tr_b16 v[156:157], v179 offset:26112
	v_add_f32_e32 v50, v60, v50
	v_add_f32_e32 v50, v61, v50
	v_add_f32_e32 v50, v62, v50
	v_add_f32_e32 v50, v63, v50
	v_cvt_pk_bf16_f32 v122, v58, v59
	v_cvt_pk_bf16_f32 v123, v60, v61
	s_waitcnt lgkmcnt(11)
	v_mfma_f32_32x32x16_bf16 v[82:97], v[150:153], v[102:105], v[82:97]
	ds_read_b64_tr_b16 v[58:59], v179 offset:29696
	ds_read_b64_tr_b16 v[60:61], v179 offset:30208
	v_add_f32_e32 v50, v64, v50
	v_add_f32_e32 v50, v65, v50
	v_add_f32_e32 v50, v34, v50
	v_add_f32_e32 v50, v35, v50
	v_cvt_pk_bf16_f32 v124, v62, v63
	v_cvt_pk_bf16_f32 v125, v64, v65
	s_waitcnt lgkmcnt(12)
	v_mfma_f32_32x32x16_bf16 v[66:81], v[146:149], v[102:105], v[66:81]
	ds_read_b64_tr_b16 v[54:55], v179 offset:26624
	ds_read_b64_tr_b16 v[56:57], v179 offset:27136
	v_add_f32_e32 v50, v36, v50
	v_add_f32_e32 v50, v37, v50
	v_add_f32_e32 v50, v38, v50
	v_add_f32_e32 v62, v39, v50
	v_cvt_pk_bf16_f32 v118, v34, v35
	v_cvt_pk_bf16_f32 v119, v36, v37
	s_waitcnt lgkmcnt(13)
	v_mfma_f32_32x32x16_bf16 v[82:97], v[142:145], v[106:109], v[82:97]
	ds_read_b64_tr_b16 v[50:51], v179 offset:30720
	ds_read_b64_tr_b16 v[52:53], v179 offset:31232
	v_add_f32_e32 v34, v40, v62
	v_add_f32_e32 v34, v41, v34
	v_add_f32_e32 v34, v42, v34
	v_add_f32_e32 v34, v43, v34
	v_cvt_pk_bf16_f32 v120, v38, v39
	v_cvt_pk_bf16_f32 v121, v40, v41
	s_waitcnt lgkmcnt(14)
	v_mfma_f32_32x32x16_bf16 v[66:81], v[138:141], v[106:109], v[66:81]
	ds_read_b64_tr_b16 v[38:39], v179 offset:27648
	ds_read_b64_tr_b16 v[40:41], v179 offset:28160
	v_add_f32_e32 v34, v44, v34
	v_add_f32_e32 v34, v45, v34
	v_add_f32_e32 v34, v46, v34
	v_add_f32_e32 v62, v47, v34
	v_cvt_pk_bf16_f32 v114, v42, v43
	v_cvt_pk_bf16_f32 v115, v44, v45
	s_waitcnt lgkmcnt(14)
	v_mfma_f32_32x32x16_bf16 v[82:97], v[134:137], v[110:113], v[82:97]
	ds_read_b64_tr_b16 v[34:35], v179 offset:31744
	ds_read_b64_tr_b16 v[36:37], v179 offset:32256
	v_add_f32_e32 v42, v48, v62
	v_add_f32_e32 v42, v49, v42
	v_add_f32_e32 v179, 0, v42
	v_cvt_pk_bf16_f32 v116, v46, v47
	v_cvt_pk_bf16_f32 v117, v48, v49
	v_mfma_f32_32x32x16_bf16 v[66:81], v[130:133], v[110:113], v[66:81]
	v_lshl_add_u64 v[42:43], v[172:173], 0, s[12:13]
	s_add_i32 s1, s73, s67
	s_mov_b32 s3, m0
	s_mov_b32 m0, s1
	s_nop 0
	global_load_lds_dwordx4 v[42:43], off
	s_mov_b32 m0, s3
	v_lshl_add_u64 v[42:43], v[170:171], 0, s[12:13]
	s_add_i32 s1, s29, s33
	s_mov_b32 s3, m0
	s_mov_b32 m0, s1
	s_nop 0
	global_load_lds_dwordx4 v[42:43], off
	s_mov_b32 m0, s3
	v_exp_f32_e32 v82, v82
	v_exp_f32_e32 v83, v83
	v_exp_f32_e32 v84, v84
	v_exp_f32_e32 v85, v85
	s_waitcnt lgkmcnt(14)
	v_mfma_f32_32x32x16_bf16 v[18:33], v[126:129], v[162:165], v[18:33]
	v_exp_f32_e32 v86, v86
	v_exp_f32_e32 v87, v87
	v_exp_f32_e32 v88, v88
	v_exp_f32_e32 v89, v89
	s_waitcnt lgkmcnt(12)
	v_mfma_f32_32x32x16_bf16 v[2:17], v[126:129], v[158:161], v[2:17]
	v_add_u32_e32 v42, s29, v196
	ds_read_b128 v[162:165], v42
	ds_read_b128 v[150:153], v42 offset:512
	v_exp_f32_e32 v90, v90
	v_exp_f32_e32 v91, v91
	v_exp_f32_e32 v92, v92
	v_exp_f32_e32 v93, v93
	s_waitcnt lgkmcnt(12)
	v_mfma_f32_32x32x16_bf16 v[18:33], v[122:125], v[154:157], v[18:33]
	ds_read_b128 v[154:157], v42 offset:2048
	ds_read_b128 v[142:145], v42 offset:2560
	v_exp_f32_e32 v94, v94
	v_exp_f32_e32 v95, v95
	v_exp_f32_e32 v96, v96
	v_exp_f32_e32 v97, v97
	s_waitcnt lgkmcnt(12)
	v_mfma_f32_32x32x16_bf16 v[2:17], v[122:125], v[58:61], v[2:17]
	ds_read_b128 v[146:149], v42 offset:4096
	ds_read_b128 v[134:137], v42 offset:4608
	v_exp_f32_e32 v66, v66
	v_exp_f32_e32 v67, v67
	v_exp_f32_e32 v68, v68
	v_exp_f32_e32 v69, v69
	s_waitcnt lgkmcnt(12)
	v_mfma_f32_32x32x16_bf16 v[18:33], v[118:121], v[54:57], v[18:33]
	ds_read_b128 v[138:141], v42 offset:6144
	ds_read_b128 v[130:133], v42 offset:6656
	v_exp_f32_e32 v70, v70
	v_exp_f32_e32 v71, v71
	v_exp_f32_e32 v72, v72
	v_exp_f32_e32 v73, v73
	s_waitcnt lgkmcnt(12)
	v_mfma_f32_32x32x16_bf16 v[2:17], v[118:121], v[50:53], v[2:17]
	v_exp_f32_e32 v74, v74
	v_exp_f32_e32 v75, v75
	v_exp_f32_e32 v76, v76
	v_exp_f32_e32 v77, v77
	s_waitcnt lgkmcnt(10)
	v_mfma_f32_32x32x16_bf16 v[18:33], v[114:117], v[38:41], v[18:33]
	v_exp_f32_e32 v78, v78
	v_exp_f32_e32 v79, v79
	v_exp_f32_e32 v80, v80
	v_exp_f32_e32 v81, v81
	s_waitcnt lgkmcnt(8)
	v_mfma_f32_32x32x16_bf16 v[2:17], v[114:117], v[34:37], v[2:17]
	s_waitcnt vmcnt(2) lgkmcnt(0)
	s_barrier
; #define WAIT_BAR(N) asm volatile("s_waitcnt vmcnt(" #N ") lgkmcnt(0)\n\ts_barrier":::"memory")
;   #define RESC() do{ if(resc){ asm volatile("s_waitcnt lgkmcnt(0)":::"memory"); \
;       _Pragma("unroll") for(int d_=0;d_<2;++d_) _Pragma("unroll") for(int r=0;r<16;++r)o[d_][r]*=wsf[crow(r,hi)]; } }while(0)
;   #define ROT() do{sl_prev=sl_cur;sl_cur=sl_next;sl_next=(sl_next==(NSLOT-1)*SLOTB)?0:sl_next+SLOTB;}while(0)
; template<int THRL> __device__ __forceinline__ void attn_unit(int b,int qb,const bf16*Q,const bf16*__restrict__ K,const bf16*__restrict__ V,bf16*O,char*shm,const float a2,const int t0,const float mref,bf16x8(&qr)[4],const bool pre,const bool hasnext,const int qbn,const bf16*Qn,const bf16*Kn,const int ...
;     ...
;     STEP(pB0,pB1,pA0,pA1,t,true,true,true);     WAIT_BAR(2); RESC(); ROT();
;     STEP(pA0,pA1,pB0,pB1,t+1,true,true,true);   WAIT_BAR(2); RESC(); ROT();
;   }
	s_add_i32 s1, s29, 0x2000
	v_add_f32_e32 v200, v198, v178
	v_add_f32_e32 v50, s61, v200
	v_add_f32_e32 v51, s80, v200
	v_add_f32_e32 v52, s81, v200
	v_add_f32_e32 v53, s82, v200
	v_add_f32_e32 v54, s83, v200
	v_add_f32_e32 v55, s84, v200
	v_add_f32_e32 v56, s85, v200
	v_add_f32_e32 v57, s86, v200
	v_add_f32_e32 v58, s87, v200
	v_add_f32_e32 v59, s88, v200
	v_add_f32_e32 v60, s89, v200
	v_add_f32_e32 v61, s90, v200
	v_add_f32_e32 v62, s91, v200
	v_add_f32_e32 v63, s97, v200
	v_add_f32_e32 v64, s62, v200
	v_add_f32_e32 v65, s63, v200
	v_add_u32_e32 v178, s73, v197
	ds_read_b64_tr_b16 v[158:159], v178 offset:24576
	ds_read_b64_tr_b16 v[160:161], v178 offset:25088
	v_add_f32_e32 v34, v82, v83
	v_add_f32_e32 v34, v84, v34
	v_add_f32_e32 v34, v85, v34
	v_add_f32_e32 v34, v86, v34
	v_add_f32_e32 v114, v87, v34
	v_cvt_pk_bf16_f32 v126, v82, v83
	v_cvt_pk_bf16_f32 v127, v84, v85
	s_waitcnt lgkmcnt(9)
	v_mfma_f32_32x32x16_bf16 v[50:65], v[162:165], v[98:101], v[50:65]
	v_add_f32_e32 v49, v176, v200
	s_cmpk_lg_i32 s29, 0x4000
	v_add_f32_e32 v34, s61, v49
	v_add_f32_e32 v35, s80, v49
	v_add_f32_e32 v36, s81, v49
	v_add_f32_e32 v37, s82, v49
	v_add_f32_e32 v38, s83, v49
	v_add_f32_e32 v39, s84, v49
	v_add_f32_e32 v40, s85, v49
	v_add_f32_e32 v41, s86, v49
	v_add_f32_e32 v42, s87, v49
	v_add_f32_e32 v43, s88, v49
	v_add_f32_e32 v44, s89, v49
	v_add_f32_e32 v45, s90, v49
	v_add_f32_e32 v46, s91, v49
	v_add_f32_e32 v47, s97, v49
	v_add_f32_e32 v48, s62, v49
	v_add_f32_e32 v49, s63, v49
	s_cselect_b32 s73, s1, 0
	v_add_f32_e32 v179, v195, v179
	ds_read_b64_tr_b16 v[162:163], v178 offset:28672
	ds_read_b64_tr_b16 v[164:165], v178 offset:29184
	s_waitcnt lgkmcnt(10)
	v_mfma_f32_32x32x16_bf16 v[34:49], v[150:153], v[98:101], v[34:49]
	v_add_f32_e32 v82, v88, v114
	v_add_f32_e32 v82, v89, v82
	v_add_f32_e32 v82, v90, v82
	v_add_f32_e32 v82, v91, v82
	v_cvt_pk_bf16_f32 v128, v86, v87
	v_cvt_pk_bf16_f32 v129, v88, v89
	ds_read_b64_tr_b16 v[150:151], v178 offset:25600
	ds_read_b64_tr_b16 v[152:153], v178 offset:26112
	s_waitcnt lgkmcnt(11)
	v_mfma_f32_32x32x16_bf16 v[50:65], v[154:157], v[102:105], v[50:65]
	v_add_f32_e32 v82, v92, v82
	v_add_f32_e32 v82, v93, v82
	v_add_f32_e32 v82, v94, v82
	v_add_f32_e32 v82, v95, v82
	v_cvt_pk_bf16_f32 v122, v90, v91
	v_cvt_pk_bf16_f32 v123, v92, v93
	ds_read_b64_tr_b16 v[90:91], v178 offset:29696
	ds_read_b64_tr_b16 v[92:93], v178 offset:30208
	s_waitcnt lgkmcnt(12)
	v_mfma_f32_32x32x16_bf16 v[34:49], v[142:145], v[102:105], v[34:49]
	v_add_f32_e32 v82, v96, v82
	v_add_f32_e32 v82, v97, v82
	v_add_f32_e32 v82, v66, v82
	v_add_f32_e32 v82, v67, v82
	v_cvt_pk_bf16_f32 v124, v94, v95
	v_cvt_pk_bf16_f32 v125, v96, v97
	ds_read_b64_tr_b16 v[86:87], v178 offset:26624
	ds_read_b64_tr_b16 v[88:89], v178 offset:27136
	s_waitcnt lgkmcnt(13)
	v_mfma_f32_32x32x16_bf16 v[50:65], v[146:149], v[106:109], v[50:65]
	v_add_f32_e32 v82, v68, v82
	v_add_f32_e32 v82, v69, v82
	v_add_f32_e32 v82, v70, v82
	v_add_f32_e32 v94, v71, v82
	v_cvt_pk_bf16_f32 v118, v66, v67
	v_cvt_pk_bf16_f32 v119, v68, v69
	ds_read_b64_tr_b16 v[82:83], v178 offset:30720
	ds_read_b64_tr_b16 v[84:85], v178 offset:31232
	s_waitcnt lgkmcnt(14)
	v_mfma_f32_32x32x16_bf16 v[34:49], v[134:137], v[106:109], v[34:49]
	v_add_f32_e32 v66, v72, v94
	v_add_f32_e32 v66, v73, v66
	v_add_f32_e32 v66, v74, v66
	v_add_f32_e32 v66, v75, v66
	v_cvt_pk_bf16_f32 v120, v70, v71
	v_cvt_pk_bf16_f32 v121, v72, v73
	ds_read_b64_tr_b16 v[70:71], v178 offset:27648
	ds_read_b64_tr_b16 v[72:73], v178 offset:28160
	s_waitcnt lgkmcnt(14)
	v_mfma_f32_32x32x16_bf16 v[50:65], v[138:141], v[110:113], v[50:65]
	v_add_f32_e32 v66, v76, v66
	v_add_f32_e32 v66, v77, v66
	v_add_f32_e32 v66, v78, v66
	v_add_f32_e32 v94, v79, v66
	v_cvt_pk_bf16_f32 v114, v74, v75
	v_cvt_pk_bf16_f32 v115, v76, v77
	ds_read_b64_tr_b16 v[66:67], v178 offset:31744
	ds_read_b64_tr_b16 v[68:69], v178 offset:32256
	v_mfma_f32_32x32x16_bf16 v[34:49], v[130:133], v[110:113], v[34:49]
	v_add_f32_e32 v74, v80, v94
	v_add_f32_e32 v74, v81, v74
	v_add_f32_e32 v74, 0, v74
	v_cvt_pk_bf16_f32 v116, v78, v79
	v_cvt_pk_bf16_f32 v117, v80, v81
	s_add_i32 s1, s29, s67
	s_mov_b32 s3, m0
	s_mov_b32 m0, s1
	s_nop 0
	global_load_lds_dwordx4 v[172:173], off
	s_mov_b32 m0, s3
	s_add_i32 s1, s73, s33
	s_mov_b32 s3, m0
	s_mov_b32 m0, s1
	s_nop 0
	global_load_lds_dwordx4 v[170:171], off
	s_mov_b32 m0, s3
	v_exp_f32_e32 v50, v50
	v_exp_f32_e32 v51, v51
	v_exp_f32_e32 v52, v52
	v_exp_f32_e32 v53, v53
	s_waitcnt lgkmcnt(14)
	v_mfma_f32_32x32x16_bf16 v[18:33], v[126:129], v[158:161], v[18:33]
	v_exp_f32_e32 v54, v54
	v_exp_f32_e32 v55, v55
	v_exp_f32_e32 v56, v56
	v_exp_f32_e32 v57, v57
	s_waitcnt lgkmcnt(12)
	v_mfma_f32_32x32x16_bf16 v[2:17], v[126:129], v[162:165], v[2:17]
	v_add_u32_e32 v75, s73, v196
	ds_read_b128 v[158:161], v75
	ds_read_b128 v[154:157], v75 offset:512
	v_exp_f32_e32 v58, v58
	v_exp_f32_e32 v59, v59
	v_exp_f32_e32 v60, v60
	v_exp_f32_e32 v61, v61
	s_waitcnt lgkmcnt(12)
	v_mfma_f32_32x32x16_bf16 v[18:33], v[122:125], v[150:153], v[18:33]
	ds_read_b128 v[150:153], v75 offset:2048
	ds_read_b128 v[146:149], v75 offset:2560
	v_exp_f32_e32 v62, v62
	v_exp_f32_e32 v63, v63
	v_exp_f32_e32 v64, v64
	v_exp_f32_e32 v65, v65
	s_waitcnt lgkmcnt(12)
	v_mfma_f32_32x32x16_bf16 v[2:17], v[122:125], v[90:93], v[2:17]
	ds_read_b128 v[142:145], v75 offset:4096
	ds_read_b128 v[138:141], v75 offset:4608
	v_exp_f32_e32 v34, v34
	v_exp_f32_e32 v35, v35
	v_exp_f32_e32 v36, v36
	v_exp_f32_e32 v37, v37
	s_waitcnt lgkmcnt(12)
	v_mfma_f32_32x32x16_bf16 v[18:33], v[118:121], v[86:89], v[18:33]
	ds_read_b128 v[134:137], v75 offset:6144
	ds_read_b128 v[130:133], v75 offset:6656
	v_exp_f32_e32 v38, v38
	v_exp_f32_e32 v39, v39
	v_exp_f32_e32 v40, v40
	v_exp_f32_e32 v41, v41
	s_waitcnt lgkmcnt(12)
	v_mfma_f32_32x32x16_bf16 v[2:17], v[118:121], v[82:85], v[2:17]
	v_exp_f32_e32 v42, v42
	v_exp_f32_e32 v43, v43
	v_exp_f32_e32 v44, v44
	v_exp_f32_e32 v45, v45
	s_waitcnt lgkmcnt(10)
	v_mfma_f32_32x32x16_bf16 v[18:33], v[114:117], v[70:73], v[18:33]
	v_exp_f32_e32 v46, v46
	v_exp_f32_e32 v47, v47
	v_exp_f32_e32 v48, v48
	v_exp_f32_e32 v49, v49
	s_waitcnt lgkmcnt(8)
	v_mfma_f32_32x32x16_bf16 v[2:17], v[114:117], v[66:69], v[2:17]
	s_add_i32 s1, s73, 0x2000
	s_waitcnt vmcnt(2) lgkmcnt(0)
	s_barrier
	s_cmpk_lg_i32 s73, 0x4000
	s_cselect_b32 s1, s1, 0
	s_add_i32 s2, s2, 2
	v_add_f32_e32 v195, v179, v74
	v_lshl_add_u64 v[170:171], v[170:171], 0, s[8:9]
	v_lshl_add_u64 v[172:173], v[172:173], 0, s[8:9]
	s_cmp_ge_i32 s2, s0
	s_mov_b32 s3, s29
	s_cbranch_scc0 .LBB0_433
	s_add_i32 s2, s2, -5
	v_lshlrev_b32_e32 v199, 9, v186
	s_add_i32 s3, s2, 1
	s_cmp_ge_i32 s3, s0
	s_cbranch_scc0 .LBB0_437

;   #define RESC() do{ if(resc){ asm volatile("s_waitcnt lgkmcnt(0)":::"memory"); \
;       _Pragma("unroll") for(int d_=0;d_<2;++d_) _Pragma("unroll") for(int r=0;r<16;++r)o[d_][r]*=wsf[crow(r,hi)]; } }while(0)
;   #define ROT() do{sl_prev=sl_cur;sl_cur=sl_next;sl_next=(sl_next==(NSLOT-1)*SLOTB)?0:sl_next+SLOTB;}while(0)
;   #define ENDW(tt) do{ if((tt)+3<NT){WAIT_BAR(2);} else if((tt)+2<NT){WAIT_BAR(1);} else {WAIT_BAR(0);} }while(0)
; template<int THRL> __device__ __forceinline__ void attn_unit(int b,int qb,const bf16*Q,const bf16*__restrict__ K,const bf16*__restrict__ V,bf16*O,char*shm,const float a2,const int t0,const float mref,bf16x8(&qr)[4],const bool pre,const bool hasnext,const int qbn,const bf16*Qn,const bf16*Kn,const int ...
;     ...
;   for(;t+1<NT;t+=2){
;     STEP(pB0,pB1,pA0,pA1,t,(t+3<NT),(t+1<NT),(t+1<NT));       ENDW(t);   RESC(); ROT();
.LBB0_438:
	v_add_f32_e32 v170, v198, v200
	v_add_f32_e32 v82, s61, v170
	v_add_f32_e32 v83, s80, v170
	v_add_f32_e32 v84, s81, v170
	v_add_f32_e32 v85, s82, v170
	v_add_f32_e32 v86, s83, v170
	v_add_f32_e32 v87, s84, v170
	v_add_f32_e32 v88, s85, v170
	v_add_f32_e32 v89, s86, v170
	v_add_f32_e32 v90, s87, v170
	v_add_f32_e32 v91, s88, v170
	v_add_f32_e32 v92, s89, v170
	v_add_f32_e32 v93, s90, v170
	v_add_f32_e32 v94, s91, v170
	v_add_f32_e32 v95, s97, v170
	v_add_f32_e32 v96, s62, v170
	v_add_f32_e32 v97, s63, v170
	v_add_u32_e32 v171, s29, v197
	ds_read_b64_tr_b16 v[162:163], v171 offset:24576
	ds_read_b64_tr_b16 v[164:165], v171 offset:25088
	v_add_f32_e32 v66, v50, v51
	v_add_f32_e32 v66, v52, v66
	v_add_f32_e32 v66, v53, v66
	v_add_f32_e32 v66, v54, v66
	v_add_f32_e32 v114, v55, v66
	v_cvt_pk_bf16_f32 v126, v50, v51
	v_cvt_pk_bf16_f32 v127, v52, v53
	s_waitcnt lgkmcnt(9)
	v_mfma_f32_32x32x16_bf16 v[82:97], v[158:161], v[98:101], v[82:97]
	v_add_f32_e32 v50, v176, v170
	v_add_f32_e32 v66, s61, v50
	v_add_f32_e32 v67, s80, v50
	v_add_f32_e32 v68, s81, v50
	v_add_f32_e32 v69, s82, v50
	v_add_f32_e32 v70, s83, v50
	v_add_f32_e32 v71, s84, v50
	v_add_f32_e32 v72, s85, v50
	v_add_f32_e32 v73, s86, v50
	v_add_f32_e32 v74, s87, v50
	v_add_f32_e32 v75, s88, v50
	v_add_f32_e32 v76, s89, v50
	v_add_f32_e32 v77, s90, v50
	v_add_f32_e32 v78, s91, v50
	v_add_f32_e32 v79, s97, v50
	v_add_f32_e32 v80, s62, v50
	v_add_f32_e32 v81, s63, v50
	ds_read_b64_tr_b16 v[158:159], v171 offset:28672
	ds_read_b64_tr_b16 v[160:161], v171 offset:29184
	s_waitcnt lgkmcnt(10)
	v_mfma_f32_32x32x16_bf16 v[66:81], v[154:157], v[98:101], v[66:81]
	v_add_f32_e32 v50, v56, v114
	v_add_f32_e32 v50, v57, v50
	v_add_f32_e32 v50, v58, v50
	v_add_f32_e32 v50, v59, v50
	v_cvt_pk_bf16_f32 v128, v54, v55
	v_cvt_pk_bf16_f32 v129, v56, v57
	ds_read_b64_tr_b16 v[166:167], v171 offset:25600
	ds_read_b64_tr_b16 v[168:169], v171 offset:26112
	s_waitcnt lgkmcnt(11)
	v_mfma_f32_32x32x16_bf16 v[82:97], v[150:153], v[102:105], v[82:97]
	v_add_f32_e32 v50, v60, v50
	v_add_f32_e32 v50, v61, v50
	v_add_f32_e32 v50, v62, v50
	v_add_f32_e32 v50, v63, v50
	v_cvt_pk_bf16_f32 v122, v58, v59
	v_cvt_pk_bf16_f32 v123, v60, v61
	ds_read_b64_tr_b16 v[58:59], v171 offset:29696
	ds_read_b64_tr_b16 v[60:61], v171 offset:30208
	s_waitcnt lgkmcnt(12)
	v_mfma_f32_32x32x16_bf16 v[66:81], v[146:149], v[102:105], v[66:81]
	v_add_f32_e32 v50, v64, v50
	v_add_f32_e32 v50, v65, v50
	v_add_f32_e32 v50, v34, v50
	v_add_f32_e32 v50, v35, v50
	v_cvt_pk_bf16_f32 v124, v62, v63
	v_cvt_pk_bf16_f32 v125, v64, v65
	ds_read_b64_tr_b16 v[54:55], v171 offset:26624
	ds_read_b64_tr_b16 v[56:57], v171 offset:27136
	s_waitcnt lgkmcnt(13)
	v_mfma_f32_32x32x16_bf16 v[82:97], v[142:145], v[106:109], v[82:97]
	v_add_f32_e32 v50, v36, v50
	v_add_f32_e32 v50, v37, v50
	v_add_f32_e32 v50, v38, v50
	v_add_f32_e32 v62, v39, v50
	v_cvt_pk_bf16_f32 v118, v34, v35
	v_cvt_pk_bf16_f32 v119, v36, v37
	ds_read_b64_tr_b16 v[50:51], v171 offset:30720
	ds_read_b64_tr_b16 v[52:53], v171 offset:31232
	s_waitcnt lgkmcnt(14)
	v_mfma_f32_32x32x16_bf16 v[66:81], v[138:141], v[106:109], v[66:81]
	v_add_f32_e32 v34, v40, v62
	v_add_f32_e32 v34, v41, v34
	v_add_f32_e32 v34, v42, v34
	v_add_f32_e32 v34, v43, v34
	v_cvt_pk_bf16_f32 v120, v38, v39
	v_cvt_pk_bf16_f32 v121, v40, v41
	ds_read_b64_tr_b16 v[38:39], v171 offset:27648
	ds_read_b64_tr_b16 v[40:41], v171 offset:28160
	s_waitcnt lgkmcnt(14)
	v_mfma_f32_32x32x16_bf16 v[82:97], v[134:137], v[110:113], v[82:97]
	v_add_f32_e32 v34, v44, v34
	v_add_f32_e32 v34, v45, v34
	v_add_f32_e32 v34, v46, v34
	v_add_f32_e32 v62, v47, v34
	v_cvt_pk_bf16_f32 v114, v42, v43
	v_cvt_pk_bf16_f32 v115, v44, v45
	ds_read_b64_tr_b16 v[34:35], v171 offset:31744
	ds_read_b64_tr_b16 v[36:37], v171 offset:32256
	v_mfma_f32_32x32x16_bf16 v[66:81], v[130:133], v[110:113], v[66:81]
	v_add_f32_e32 v42, v48, v62
	v_add_f32_e32 v42, v49, v42
	v_add_f32_e32 v201, 0, v42
	v_cvt_pk_bf16_f32 v116, v46, v47
	v_cvt_pk_bf16_f32 v117, v48, v49
	s_add_i32 s2, s93, 1
	s_cmp_ge_i32 s2, s0
	s_cselect_b64 s[26:27], -1, 0
	s_and_b64 vcc, exec, s[26:27]
	s_cbranch_vccnz .LBB0_440
	v_lshl_add_u64 v[42:43], v[180:181], 0, s[12:13]
	s_add_i32 s2, s73, s67
	s_mov_b32 s3, m0
	s_mov_b32 m0, s2
	s_nop 0
	global_load_lds_dwordx4 v[42:43], off
	s_mov_b32 m0, s3

.LBB0_442:
	v_exp_f32_e32 v82, v82
	v_exp_f32_e32 v83, v83
	v_exp_f32_e32 v84, v84
	v_exp_f32_e32 v85, v85
	s_waitcnt lgkmcnt(14)
	v_mfma_f32_32x32x16_bf16 v[18:33], v[126:129], v[162:165], v[18:33]
	v_exp_f32_e32 v86, v86
	v_exp_f32_e32 v87, v87
	v_exp_f32_e32 v88, v88
	v_exp_f32_e32 v89, v89
	s_waitcnt lgkmcnt(12)
	v_mfma_f32_32x32x16_bf16 v[2:17], v[126:129], v[158:161], v[2:17]
	v_add_u32_e32 v42, s1, v196
	ds_read_b128 v[158:161], v42
	ds_read_b128 v[154:157], v42 offset:512
	v_exp_f32_e32 v90, v90
	v_exp_f32_e32 v91, v91
	v_exp_f32_e32 v92, v92
	v_exp_f32_e32 v93, v93
	s_waitcnt lgkmcnt(12)
	v_mfma_f32_32x32x16_bf16 v[18:33], v[122:125], v[166:169], v[18:33]
	ds_read_b128 v[150:153], v42 offset:2048
	ds_read_b128 v[146:149], v42 offset:2560
	v_exp_f32_e32 v94, v94
	v_exp_f32_e32 v95, v95
	v_exp_f32_e32 v96, v96
	v_exp_f32_e32 v97, v97
	s_waitcnt lgkmcnt(12)
	v_mfma_f32_32x32x16_bf16 v[2:17], v[122:125], v[58:61], v[2:17]
	ds_read_b128 v[142:145], v42 offset:4096
	ds_read_b128 v[138:141], v42 offset:4608
	v_exp_f32_e32 v66, v66
	v_exp_f32_e32 v67, v67
	v_exp_f32_e32 v68, v68
	v_exp_f32_e32 v69, v69
	s_waitcnt lgkmcnt(12)
	v_mfma_f32_32x32x16_bf16 v[18:33], v[118:121], v[54:57], v[18:33]
	ds_read_b128 v[134:137], v42 offset:6144
	ds_read_b128 v[130:133], v42 offset:6656
	v_exp_f32_e32 v70, v70
	v_exp_f32_e32 v71, v71
	v_exp_f32_e32 v72, v72
	v_exp_f32_e32 v73, v73
	s_waitcnt lgkmcnt(12)
	v_mfma_f32_32x32x16_bf16 v[2:17], v[118:121], v[50:53], v[2:17]
	v_exp_f32_e32 v74, v74
	v_exp_f32_e32 v75, v75
	v_exp_f32_e32 v76, v76
	v_exp_f32_e32 v77, v77
	s_waitcnt lgkmcnt(10)
	v_mfma_f32_32x32x16_bf16 v[18:33], v[114:117], v[38:41], v[18:33]
	v_exp_f32_e32 v78, v78
	v_exp_f32_e32 v79, v79
	v_exp_f32_e32 v80, v80
	v_exp_f32_e32 v81, v81
	s_waitcnt lgkmcnt(8)
	v_mfma_f32_32x32x16_bf16 v[2:17], v[114:117], v[34:37], v[2:17]
	s_mov_b64 s[2:3], -1
	s_and_b64 vcc, exec, s[26:27]
	s_cbranch_vccz .LBB0_448
	s_cmp_ge_i32 s93, s0
	s_cbranch_scc0 .LBB0_445
	s_waitcnt vmcnt(0) lgkmcnt(0)
	s_barrier
	s_mov_b64 s[2:3], 0

;   #define RESC() do{ if(resc){ asm volatile("s_waitcnt lgkmcnt(0)":::"memory"); \
;       _Pragma("unroll") for(int d_=0;d_<2;++d_) _Pragma("unroll") for(int r=0;r<16;++r)o[d_][r]*=wsf[crow(r,hi)]; } }while(0)
;   #define ROT() do{sl_prev=sl_cur;sl_cur=sl_next;sl_next=(sl_next==(NSLOT-1)*SLOTB)?0:sl_next+SLOTB;}while(0)
;   #define ENDW(tt) do{ if((tt)+3<NT){WAIT_BAR(2);} else if((tt)+2<NT){WAIT_BAR(1);} else {WAIT_BAR(0);} }while(0)
; template<int THRL> __device__ __forceinline__ void attn_unit(int b,int qb,const bf16*Q,const bf16*__restrict__ K,const bf16*__restrict__ V,bf16*O,char*shm,const float a2,const int t0,const float mref,bf16x8(&qr)[4],const bool pre,const bool hasnext,const int qbn,const bf16*Qn,const bf16*Kn,const int ...
;     ...
;     STEP(pA0,pA1,pB0,pB1,t+1,(t+4<NT),(t+2<NT),(t+2<NT));     ENDW(t+1); RESC(); ROT();
.LBB0_450:
	v_add_f32_e32 v200, v198, v170
	v_add_f32_e32 v50, s61, v200
	v_add_f32_e32 v51, s80, v200
	v_add_f32_e32 v52, s81, v200
	v_add_f32_e32 v53, s82, v200
	v_add_f32_e32 v54, s83, v200
	v_add_f32_e32 v55, s84, v200
	v_add_f32_e32 v56, s85, v200
	v_add_f32_e32 v57, s86, v200
	v_add_f32_e32 v58, s87, v200
	v_add_f32_e32 v59, s88, v200
	v_add_f32_e32 v60, s89, v200
	v_add_f32_e32 v61, s90, v200
	v_add_f32_e32 v62, s91, v200
	v_add_f32_e32 v63, s97, v200
	v_add_f32_e32 v64, s62, v200
	v_add_f32_e32 v65, s63, v200
	v_add_u32_e32 v202, s73, v197
	ds_read_b64_tr_b16 v[162:163], v202 offset:24576
	ds_read_b64_tr_b16 v[164:165], v202 offset:25088
	v_add_f32_e32 v34, v82, v83
	v_add_f32_e32 v34, v84, v34
	v_add_f32_e32 v34, v85, v34
	v_add_f32_e32 v34, v86, v34
	v_add_f32_e32 v114, v87, v34
	v_cvt_pk_bf16_f32 v126, v82, v83
	v_cvt_pk_bf16_f32 v127, v84, v85
	s_waitcnt lgkmcnt(9)
	v_mfma_f32_32x32x16_bf16 v[50:65], v[158:161], v[98:101], v[50:65]
	v_add_f32_e32 v49, v176, v200
	v_add_f32_e32 v34, s61, v49
	v_add_f32_e32 v35, s80, v49
	v_add_f32_e32 v36, s81, v49
	v_add_f32_e32 v37, s82, v49
	v_add_f32_e32 v38, s83, v49
	v_add_f32_e32 v39, s84, v49
	v_add_f32_e32 v40, s85, v49
	v_add_f32_e32 v41, s86, v49
	v_add_f32_e32 v42, s87, v49
	v_add_f32_e32 v43, s88, v49
	v_add_f32_e32 v44, s89, v49
	v_add_f32_e32 v45, s90, v49
	v_add_f32_e32 v46, s91, v49
	v_add_f32_e32 v47, s97, v49
	v_add_f32_e32 v48, s62, v49
	v_add_f32_e32 v49, s63, v49
	ds_read_b64_tr_b16 v[170:171], v202 offset:28672
	ds_read_b64_tr_b16 v[172:173], v202 offset:29184
	s_waitcnt lgkmcnt(10)
	v_mfma_f32_32x32x16_bf16 v[34:49], v[154:157], v[98:101], v[34:49]
	v_add_f32_e32 v82, v88, v114
	v_add_f32_e32 v82, v89, v82
	v_add_f32_e32 v82, v90, v82
	v_add_f32_e32 v82, v91, v82
	v_cvt_pk_bf16_f32 v128, v86, v87
	v_cvt_pk_bf16_f32 v129, v88, v89
	ds_read_b64_tr_b16 v[166:167], v202 offset:25600
	ds_read_b64_tr_b16 v[168:169], v202 offset:26112
	s_waitcnt lgkmcnt(11)
	v_mfma_f32_32x32x16_bf16 v[50:65], v[150:153], v[102:105], v[50:65]
	v_add_f32_e32 v82, v92, v82
	v_add_f32_e32 v82, v93, v82
	v_add_f32_e32 v82, v94, v82
	v_add_f32_e32 v82, v95, v82
	v_cvt_pk_bf16_f32 v122, v90, v91
	v_cvt_pk_bf16_f32 v123, v92, v93
	ds_read_b64_tr_b16 v[90:91], v202 offset:29696
	ds_read_b64_tr_b16 v[92:93], v202 offset:30208
	s_waitcnt lgkmcnt(12)
	v_mfma_f32_32x32x16_bf16 v[34:49], v[146:149], v[102:105], v[34:49]
	v_add_f32_e32 v82, v96, v82
	v_add_f32_e32 v82, v97, v82
	v_add_f32_e32 v82, v66, v82
	v_add_f32_e32 v82, v67, v82
	v_cvt_pk_bf16_f32 v124, v94, v95
	v_cvt_pk_bf16_f32 v125, v96, v97
	ds_read_b64_tr_b16 v[86:87], v202 offset:26624
	ds_read_b64_tr_b16 v[88:89], v202 offset:27136
	s_waitcnt lgkmcnt(13)
	v_mfma_f32_32x32x16_bf16 v[50:65], v[142:145], v[106:109], v[50:65]
	v_add_f32_e32 v82, v68, v82
	v_add_f32_e32 v82, v69, v82
	v_add_f32_e32 v82, v70, v82
	v_add_f32_e32 v94, v71, v82
	v_cvt_pk_bf16_f32 v118, v66, v67
	v_cvt_pk_bf16_f32 v119, v68, v69
	ds_read_b64_tr_b16 v[82:83], v202 offset:30720
	ds_read_b64_tr_b16 v[84:85], v202 offset:31232
	s_waitcnt lgkmcnt(14)
	v_mfma_f32_32x32x16_bf16 v[34:49], v[138:141], v[106:109], v[34:49]
	v_add_f32_e32 v66, v72, v94
	v_add_f32_e32 v66, v73, v66
	v_add_f32_e32 v66, v74, v66
	v_add_f32_e32 v66, v75, v66
	v_cvt_pk_bf16_f32 v120, v70, v71
	v_cvt_pk_bf16_f32 v121, v72, v73
	ds_read_b64_tr_b16 v[70:71], v202 offset:27648
	ds_read_b64_tr_b16 v[72:73], v202 offset:28160
	s_waitcnt lgkmcnt(14)
	v_mfma_f32_32x32x16_bf16 v[50:65], v[134:137], v[110:113], v[50:65]
	v_add_f32_e32 v66, v76, v66
	v_add_f32_e32 v66, v77, v66
	v_add_f32_e32 v66, v78, v66
	v_add_f32_e32 v94, v79, v66
	v_cvt_pk_bf16_f32 v114, v74, v75
	v_cvt_pk_bf16_f32 v115, v76, v77
	ds_read_b64_tr_b16 v[66:67], v202 offset:31744
	ds_read_b64_tr_b16 v[68:69], v202 offset:32256
	v_mfma_f32_32x32x16_bf16 v[34:49], v[130:133], v[110:113], v[34:49]
	v_add_f32_e32 v74, v80, v94
	v_add_f32_e32 v74, v81, v74
	v_add_f32_e32 v74, 0, v74
	v_cvt_pk_bf16_f32 v116, v78, v79
	v_cvt_pk_bf16_f32 v117, v80, v81
	s_add_i32 s68, s93, 2
	s_cmp_ge_i32 s68, s0
	s_cselect_b64 s[28:29], -1, 0
	s_and_b64 vcc, exec, s[28:29]
	s_cbranch_vccnz .LBB0_452
	s_add_i32 s2, s1, s67
	s_mov_b32 s3, m0
	s_mov_b32 m0, s2
	s_nop 0
	global_load_lds_dwordx4 v[180:181], off
	s_mov_b32 m0, s3

.LBB0_456:
	v_exp_f32_e32 v50, v50
	v_exp_f32_e32 v51, v51
	v_exp_f32_e32 v52, v52
	v_exp_f32_e32 v53, v53
	s_waitcnt lgkmcnt(14)
	v_mfma_f32_32x32x16_bf16 v[18:33], v[126:129], v[162:165], v[18:33]
	v_exp_f32_e32 v54, v54
	v_exp_f32_e32 v55, v55
	v_exp_f32_e32 v56, v56
	v_exp_f32_e32 v57, v57
	s_waitcnt lgkmcnt(12)
	v_mfma_f32_32x32x16_bf16 v[2:17], v[126:129], v[170:173], v[2:17]
	v_cndmask_b32_e64 v75, 0, 1, s[30:31]
	v_cmp_ne_u32_e64 s[2:3], 1, v75
	s_andn2_b64 vcc, exec, s[30:31]
	v_add_u32_e32 v75, s73, v196
	s_cbranch_vccnz .LBB0_458
	ds_read_b128 v[158:161], v75
	ds_read_b128 v[154:157], v75 offset:512

.LBB0_464:
	v_exp_f32_e32 v38, v38
	v_exp_f32_e32 v39, v39
	v_exp_f32_e32 v40, v40
	v_exp_f32_e32 v41, v41
	s_waitcnt lgkmcnt(4)
	v_mfma_f32_32x32x16_bf16 v[2:17], v[118:121], v[82:85], v[2:17]
	v_exp_f32_e32 v42, v42
	v_exp_f32_e32 v43, v43
	v_exp_f32_e32 v44, v44
	v_exp_f32_e32 v45, v45
	s_waitcnt lgkmcnt(2)
	v_mfma_f32_32x32x16_bf16 v[18:33], v[114:117], v[70:73], v[18:33]
	v_exp_f32_e32 v46, v46
	v_exp_f32_e32 v47, v47
	v_exp_f32_e32 v48, v48
	v_exp_f32_e32 v49, v49
	s_waitcnt lgkmcnt(0)
	v_mfma_f32_32x32x16_bf16 v[2:17], v[114:117], v[66:69], v[2:17]
	s_mov_b64 s[2:3], -1
	s_and_b64 vcc, exec, s[28:29]
	s_cbranch_vccz .LBB0_470
	s_and_b64 vcc, exec, s[26:27]
	s_cbranch_vccz .LBB0_467
	s_waitcnt vmcnt(0) lgkmcnt(0)
	s_barrier
	s_mov_b64 s[2:3], 0

; __device__ __forceinline__ void cmask(f32x16&p0,f32x16&p1,int jb,int qrel,int hi){
;   const float NEG=-INFINITY; int kb=64*jb+4*hi;
;   #pragma unroll
;   for(int r=0;r<16;++r){int kv=kb+(r&3)+8*(r>>2); if(kv>qrel)p0[r]=NEG; if(kv+32>qrel)p1[r]=NEG;}
; }
.LBB0_475:
	v_add_f32_e32 v82, v198, v200
	v_add_f32_e32 v66, s61, v82
	v_add_f32_e32 v67, s80, v82
	v_add_f32_e32 v68, s81, v82
	v_add_f32_e32 v69, s82, v82
	v_add_f32_e32 v70, s83, v82
	v_add_f32_e32 v71, s84, v82
	v_add_f32_e32 v72, s85, v82
	v_add_f32_e32 v73, s86, v82
	v_add_f32_e32 v74, s87, v82
	v_add_f32_e32 v75, s88, v82
	v_add_f32_e32 v76, s89, v82
	v_add_f32_e32 v77, s90, v82
	v_add_f32_e32 v78, s91, v82
	v_add_f32_e32 v79, s97, v82
	v_add_f32_e32 v80, s62, v82
	v_add_f32_e32 v81, s63, v82
	v_add_u32_e32 v166, s1, v197
	ds_read_b64_tr_b16 v[162:163], v166 offset:24576
	ds_read_b64_tr_b16 v[164:165], v166 offset:25088
	v_add_f32_e32 v83, v50, v51
	v_add_f32_e32 v83, v52, v83
	v_add_f32_e32 v83, v53, v83
	v_add_f32_e32 v83, v54, v83
	v_add_f32_e32 v114, v55, v83
	v_cvt_pk_bf16_f32 v126, v50, v51
	v_cvt_pk_bf16_f32 v127, v52, v53
	v_add_f32_e32 v50, v176, v82
	v_add_f32_e32 v82, s61, v50
	v_add_f32_e32 v83, s80, v50
	v_add_f32_e32 v84, s81, v50
	v_add_f32_e32 v85, s82, v50
	v_add_f32_e32 v86, s83, v50
	v_add_f32_e32 v87, s84, v50
	v_add_f32_e32 v88, s85, v50
	v_add_f32_e32 v89, s86, v50
	v_add_f32_e32 v90, s87, v50
	v_add_f32_e32 v91, s88, v50
	v_add_f32_e32 v92, s89, v50
	v_add_f32_e32 v93, s90, v50
	v_add_f32_e32 v94, s91, v50
	v_add_f32_e32 v95, s97, v50
	v_add_f32_e32 v96, s62, v50
	v_add_f32_e32 v97, s63, v50
	s_waitcnt lgkmcnt(9)
	v_mfma_f32_32x32x16_bf16 v[66:81], v[158:161], v[98:101], v[66:81]
	ds_read_b64_tr_b16 v[158:159], v166 offset:28672
	ds_read_b64_tr_b16 v[160:161], v166 offset:29184
	v_add_f32_e32 v50, v56, v114
	v_add_f32_e32 v50, v57, v50
	v_add_f32_e32 v50, v58, v50
	v_add_f32_e32 v50, v59, v50
	v_cvt_pk_bf16_f32 v128, v54, v55
	v_cvt_pk_bf16_f32 v129, v56, v57
	s_waitcnt lgkmcnt(10)
	v_mfma_f32_32x32x16_bf16 v[82:97], v[154:157], v[98:101], v[82:97]
	ds_read_b64_tr_b16 v[154:155], v166 offset:25600
	ds_read_b64_tr_b16 v[156:157], v166 offset:26112
	v_add_f32_e32 v50, v60, v50
	v_add_f32_e32 v50, v61, v50
	v_add_f32_e32 v50, v62, v50
	v_add_f32_e32 v50, v63, v50
	v_cvt_pk_bf16_f32 v122, v58, v59
	v_cvt_pk_bf16_f32 v123, v60, v61
	s_waitcnt lgkmcnt(11)
	v_mfma_f32_32x32x16_bf16 v[66:81], v[150:153], v[102:105], v[66:81]
	ds_read_b64_tr_b16 v[150:151], v166 offset:29696
	ds_read_b64_tr_b16 v[152:153], v166 offset:30208
	v_add_f32_e32 v50, v64, v50
	v_add_f32_e32 v50, v65, v50
	v_add_f32_e32 v50, v34, v50
	v_add_f32_e32 v50, v35, v50
	v_cvt_pk_bf16_f32 v124, v62, v63
	v_cvt_pk_bf16_f32 v125, v64, v65
	s_waitcnt lgkmcnt(12)
	v_mfma_f32_32x32x16_bf16 v[82:97], v[146:149], v[102:105], v[82:97]
	ds_read_b64_tr_b16 v[146:147], v166 offset:26624
	ds_read_b64_tr_b16 v[148:149], v166 offset:27136
	v_add_f32_e32 v50, v36, v50
	v_add_f32_e32 v50, v37, v50
	v_add_f32_e32 v50, v38, v50
	v_add_f32_e32 v50, v39, v50
	v_cvt_pk_bf16_f32 v118, v34, v35
	v_cvt_pk_bf16_f32 v119, v36, v37
	s_waitcnt lgkmcnt(13)
	v_mfma_f32_32x32x16_bf16 v[66:81], v[142:145], v[106:109], v[66:81]
	ds_read_b64_tr_b16 v[142:143], v166 offset:30720
	ds_read_b64_tr_b16 v[144:145], v166 offset:31232
	v_add_f32_e32 v34, v40, v50
	v_add_f32_e32 v34, v41, v34
	v_add_f32_e32 v34, v42, v34
	v_add_f32_e32 v34, v43, v34
	v_cvt_pk_bf16_f32 v120, v38, v39
	v_cvt_pk_bf16_f32 v121, v40, v41
	s_waitcnt lgkmcnt(14)
	v_mfma_f32_32x32x16_bf16 v[82:97], v[138:141], v[106:109], v[82:97]
	ds_read_b64_tr_b16 v[138:139], v166 offset:27648
	ds_read_b64_tr_b16 v[140:141], v166 offset:28160
	v_add_f32_e32 v34, v44, v34
	v_add_f32_e32 v34, v45, v34
	v_add_f32_e32 v34, v46, v34
	v_add_f32_e32 v34, v47, v34
	v_cvt_pk_bf16_f32 v114, v42, v43
	v_cvt_pk_bf16_f32 v115, v44, v45
	s_waitcnt lgkmcnt(14)
	v_mfma_f32_32x32x16_bf16 v[66:81], v[134:137], v[110:113], v[66:81]
	ds_read_b64_tr_b16 v[134:135], v166 offset:31744
	ds_read_b64_tr_b16 v[136:137], v166 offset:32256
	v_add_f32_e32 v34, v48, v34
	v_add_f32_e32 v34, v49, v34
	v_mfma_f32_32x32x16_bf16 v[82:97], v[130:133], v[110:113], v[82:97]
	v_add_f32_e32 v130, 0, v34
	v_cvt_pk_bf16_f32 v116, v46, v47
	v_cvt_pk_bf16_f32 v117, v48, v49
	v_or_b32_e32 v35, 0xe0, v190
	v_or_b32_e32 v34, 0xc0, v190
	v_cmp_le_i32_e32 vcc, v35, v194
	v_or_b32_e32 v37, 0xe1, v190
	v_or_b32_e32 v38, 0xc2, v190
	s_nop 3
	v_cndmask_b32_e32 v35, v185, v82, vcc
	v_cmp_lt_i32_e32 vcc, v34, v194
	v_or_b32_e32 v39, 0xc9, v190
	v_or_b32_e32 v40, 0xca, v190
	v_cndmask_b32_e32 v36, v185, v67, vcc
	v_cmp_le_i32_e32 vcc, v34, v194
	v_or_b32_e32 v41, 0xcb, v190
	v_or_b32_e32 v42, 0xd0, v190
	v_cndmask_b32_e32 v34, v185, v66, vcc
	v_cmp_le_i32_e32 vcc, v37, v194
	v_or_b32_e32 v43, 0xd1, v190
	v_or_b32_e32 v44, 0xd2, v190
	v_cndmask_b32_e32 v37, v185, v83, vcc
	v_cmp_le_i32_e32 vcc, v38, v194
	v_or_b32_e32 v38, 0xe2, v190
	v_or_b32_e32 v45, 0xd3, v190
	v_cndmask_b32_e32 v52, v185, v68, vcc
	v_cmp_le_i32_e32 vcc, v38, v194
	v_or_b32_e32 v38, 0xc3, v190
	v_or_b32_e32 v46, 0xd8, v190
	v_cndmask_b32_e32 v66, v185, v84, vcc
	v_cmp_le_i32_e32 vcc, v38, v194
	v_or_b32_e32 v38, 0xe3, v190
	v_or_b32_e32 v47, 0xd9, v190
	v_cndmask_b32_e32 v53, v185, v69, vcc
	v_cmp_le_i32_e32 vcc, v38, v194
	v_or_b32_e32 v38, 0xc8, v190
	v_or_b32_e32 v48, 0xda, v190
	v_cndmask_b32_e32 v67, v185, v85, vcc
	v_cmp_le_i32_e32 vcc, v38, v194
	v_or_b32_e32 v38, 0xe8, v190
	v_or_b32_e32 v49, 0xdb, v190
	v_cndmask_b32_e32 v54, v185, v70, vcc
	v_cmp_le_i32_e32 vcc, v38, v194
	s_nop 1
	v_cndmask_b32_e32 v38, v185, v86, vcc
	v_cmp_le_i32_e32 vcc, v39, v194
	v_or_b32_e32 v39, 0xe9, v190
	s_nop 0
	v_cndmask_b32_e32 v55, v185, v71, vcc
	v_cmp_le_i32_e32 vcc, v39, v194
	s_nop 1
	v_cndmask_b32_e32 v39, v185, v87, vcc
	v_cmp_le_i32_e32 vcc, v40, v194
	v_or_b32_e32 v40, 0xea, v190
	s_nop 0
	v_cndmask_b32_e32 v56, v185, v72, vcc
; template<int THRL> __device__ __forceinline__ void attn_unit(int b,int qb,const bf16*Q,const bf16*__restrict__ K,const bf16*__restrict__ V,bf16*O,char*shm,const float a2,const int t0,const float mref,bf16x8(&qr)[4],const bool pre,const bool hasnext,const int qbn,const bf16*Qn,const bf16*Kn,const int ...
;     ...
;   if(hasnext){ const bf16*ksn=Kn+(rowbase+(long)t0n*KVBLK)*DM+(long)lane*DM+wid*8; const bf16*Qwn=Qn+(rowbase+(long)qbn*QB+wid*QBLK)*DM;
;     glds16(ksn,(unsigned)__builtin_amdgcn_readfirstlane(kdst)); glds16(ksn+(long)KVBLK*DM,(unsigned)__builtin_amdgcn_readfirstlane(kdst+SLOTB)); glds16(ksn+2L*KVBLK*DM,(unsigned)__builtin_amdgcn_readfirstlane(kdst+2*SLOTB));
;     _Pragma("unroll") for(int d0=0;d0<4;++d0)qr[d0]=*reinterpret_cast<const bf16x8*>(&Qwn[(long)r32*DM+d0*16+hi*8]); }
	v_cmp_le_i32_e32 vcc, v40, v194
	s_nop 1
	v_cndmask_b32_e32 v40, v185, v88, vcc
	v_cmp_le_i32_e32 vcc, v41, v194
	v_or_b32_e32 v41, 0xeb, v190
	s_nop 0
	v_cndmask_b32_e32 v57, v185, v73, vcc
	v_cmp_le_i32_e32 vcc, v41, v194
	s_nop 1
	v_cndmask_b32_e32 v41, v185, v89, vcc
	v_cmp_le_i32_e32 vcc, v42, v194
	v_or_b32_e32 v42, 0xf0, v190
	s_nop 0
	v_cndmask_b32_e32 v58, v185, v74, vcc
	v_cmp_le_i32_e32 vcc, v42, v194
	s_nop 1
	v_cndmask_b32_e32 v42, v185, v90, vcc
	v_cmp_le_i32_e32 vcc, v43, v194
	v_or_b32_e32 v43, 0xf1, v190
	s_nop 0
	v_cndmask_b32_e32 v59, v185, v75, vcc
	v_cmp_le_i32_e32 vcc, v43, v194
	s_nop 1
	v_cndmask_b32_e32 v43, v185, v91, vcc
	v_cmp_le_i32_e32 vcc, v44, v194
	v_or_b32_e32 v44, 0xf2, v190
	s_nop 0
	v_cndmask_b32_e32 v60, v185, v76, vcc
	v_cmp_le_i32_e32 vcc, v44, v194
	s_nop 1
	v_cndmask_b32_e32 v44, v185, v92, vcc
	v_cmp_le_i32_e32 vcc, v45, v194
	v_or_b32_e32 v45, 0xf3, v190
	s_nop 0
	v_cndmask_b32_e32 v61, v185, v77, vcc
	v_cmp_le_i32_e32 vcc, v45, v194
	s_nop 1
	v_cndmask_b32_e32 v45, v185, v93, vcc
	v_cmp_le_i32_e32 vcc, v46, v194
	v_or_b32_e32 v46, 0xf8, v190
	s_nop 0
	v_cndmask_b32_e32 v62, v185, v78, vcc
	v_cmp_le_i32_e32 vcc, v46, v194
	s_nop 1
	v_cndmask_b32_e32 v46, v185, v94, vcc
	v_cmp_le_i32_e32 vcc, v47, v194
	v_or_b32_e32 v47, 0xf9, v190
	s_nop 0
	v_cndmask_b32_e32 v63, v185, v79, vcc
	v_cmp_le_i32_e32 vcc, v47, v194
	s_nop 1
	v_cndmask_b32_e32 v47, v185, v95, vcc
	v_cmp_le_i32_e32 vcc, v48, v194
	v_or_b32_e32 v48, 0xfa, v190
	s_nop 0
	v_cndmask_b32_e32 v64, v185, v80, vcc
	v_cmp_le_i32_e32 vcc, v48, v194
	s_nop 1
	v_cndmask_b32_e32 v48, v185, v96, vcc
	v_cmp_le_i32_e32 vcc, v49, v194
	v_or_b32_e32 v49, 0xfb, v190
	s_nop 0
	v_cndmask_b32_e32 v65, v185, v81, vcc
	v_cmp_le_i32_e32 vcc, v49, v194
	s_nop 1
	v_cndmask_b32_e32 v49, v185, v97, vcc
	s_waitcnt lgkmcnt(14)
	v_mfma_f32_32x32x16_bf16 v[18:33], v[126:129], v[162:165], v[18:33]
	v_exp_f32_e32 v50, v34
	v_exp_f32_e32 v51, v36
	v_exp_f32_e32 v52, v52
	v_exp_f32_e32 v53, v53
	v_exp_f32_e32 v54, v54
	v_exp_f32_e32 v55, v55
	v_exp_f32_e32 v56, v56
	v_exp_f32_e32 v57, v57
	s_waitcnt lgkmcnt(12)
	v_mfma_f32_32x32x16_bf16 v[2:17], v[126:129], v[158:161], v[2:17]
	v_exp_f32_e32 v58, v58
	v_exp_f32_e32 v59, v59
	v_exp_f32_e32 v60, v60
	v_exp_f32_e32 v61, v61
	s_waitcnt lgkmcnt(10)
	v_mfma_f32_32x32x16_bf16 v[18:33], v[122:125], v[154:157], v[18:33]
	v_exp_f32_e32 v62, v62
	v_exp_f32_e32 v63, v63
	v_exp_f32_e32 v64, v64
	v_exp_f32_e32 v65, v65
	s_waitcnt lgkmcnt(8)
	v_mfma_f32_32x32x16_bf16 v[2:17], v[122:125], v[150:153], v[2:17]
	s_waitcnt lgkmcnt(6)
	v_mfma_f32_32x32x16_bf16 v[18:33], v[118:121], v[146:149], v[18:33]
	v_exp_f32_e32 v34, v35
	v_exp_f32_e32 v35, v37
	v_exp_f32_e32 v36, v66
	v_exp_f32_e32 v37, v67
	v_exp_f32_e32 v38, v38
	v_exp_f32_e32 v39, v39
	v_exp_f32_e32 v40, v40
	v_exp_f32_e32 v41, v41
	s_waitcnt lgkmcnt(4)
	v_mfma_f32_32x32x16_bf16 v[2:17], v[118:121], v[142:145], v[2:17]
	v_exp_f32_e32 v42, v42
	v_exp_f32_e32 v43, v43
	v_exp_f32_e32 v44, v44
	v_exp_f32_e32 v45, v45
	s_waitcnt lgkmcnt(2)
	v_mfma_f32_32x32x16_bf16 v[18:33], v[114:117], v[138:141], v[18:33]
	v_exp_f32_e32 v46, v46
	v_exp_f32_e32 v47, v47
	v_exp_f32_e32 v48, v48
	v_exp_f32_e32 v49, v49
	s_waitcnt lgkmcnt(0)
	v_mfma_f32_32x32x16_bf16 v[2:17], v[114:117], v[134:137], v[2:17]
	s_andn2_b64 vcc, exec, s[22:23]
	s_cbranch_vccnz .LBB0_477
	s_lshl_b32 s0, s58, 7
	s_or_b32 s0, s0, s50
	s_ashr_i32 s1, s0, 31
	s_and_b32 s4, s72, 0x7ffffffe
	s_lshl_b64 s[0:1], s[0:1], 1
	s_add_u32 s2, s34, s0
	s_addc_u32 s3, s35, s1
	s_add_u32 s22, s42, s0
	s_addc_u32 s23, s43, s1
	s_lshl_b64 s[0:1], s[4:5], 16
	s_add_u32 s0, s22, s0
	s_addc_u32 s1, s23, s1
	s_add_u32 s0, s0, s18
	s_addc_u32 s1, s1, s19
	v_lshlrev_b32_e32 v176, 1, v199
	v_lshl_add_u64 v[66:67], s[0:1], 0, v[176:177]
	s_or_b32 s0, s14, s59
	s_add_u32 s0, s0, s64
	s_addc_u32 s1, s15, s65
	s_lshl_b64 s[0:1], s[0:1], 10
	s_add_u32 s0, s2, s0
	s_addc_u32 s1, s3, s1
	v_lshl_add_u64 v[66:67], s[24:25], 1, v[66:67]
	s_mov_b32 s2, m0
	s_mov_b32 m0, s67
	s_nop 0
	global_load_lds_dwordx4 v[66:67], off
	s_mov_b32 m0, s2
	s_cmp_lg_u32 0, -1
	s_cselect_b32 s2, 0, 0
	s_add_i32 s2, s2, s66
	v_lshl_add_u64 v[68:69], v[66:67], 0, s[6:7]
	s_add_i32 s3, s2, 0x2000
	s_mov_b32 s4, m0
	s_mov_b32 m0, s3
	s_nop 0
	global_load_lds_dwordx4 v[68:69], off
	s_mov_b32 m0, s4
	v_lshl_add_u64 v[66:67], v[66:67], 0, s[8:9]
	s_addk_i32 s2, 0x4000
	s_mov_b32 s3, m0
	s_mov_b32 m0, s2
	s_nop 0
	global_load_lds_dwordx4 v[66:67], off
	s_mov_b32 m0, s3
	v_lshlrev_b32_e32 v66, 10, v187
	v_lshl_or_b32 v66, v188, 4, v66
	global_load_dwordx4 v[98:101], v66, s[0:1]
	global_load_dwordx4 v[102:105], v66, s[0:1] offset:32
	global_load_dwordx4 v[106:109], v66, s[0:1] offset:64
	global_load_dwordx4 v[110:113], v66, s[0:1] offset:96
; #define SBAR() __builtin_amdgcn_sched_barrier(0)
;   #define PKW(P,B) cvtpk_s(P[B],P[B+1])
; template<int THRL> __device__ __forceinline__ void attn_unit(int b,int qb,const bf16*Q,const bf16*__restrict__ K,const bf16*__restrict__ V,bf16*O,char*shm,const float a2,const int t0,const float mref,bf16x8(&qr)[4],const bool pre,const bool hasnext,const int qbn,const bf16*Qn,const bf16*Kn,const int ...
;     ...
;   { float sacc=pB0[0]+pB0[1]; _Pragma("unroll") for(int r=2;r<16;++r)sacc+=pB0[r]; _Pragma("unroll") for(int r=0;r<16;++r)sacc+=pB1[r]; l_reg+=sacc;
;     pw0=(u32x4){PKW(pB0,0),PKW(pB0,2),PKW(pB0,4),PKW(pB0,6)};pw1=(u32x4){PKW(pB0,8),PKW(pB0,10),PKW(pB0,12),PKW(pB0,14)};pw2=(u32x4){PKW(pB1,0),PKW(pB1,2),PKW(pB1,4),PKW(pB1,6)};pw3=(u32x4){PKW(pB1,8),PKW(pB1,10),PKW(pB1,12),PKW(pB1,14)};
;     SBAR(); pv(o,vb0+sl_cur,PAF(0),PAF(1),PAF(2),PAF(3)); }
;     ...
;   {auto rr=__builtin_amdgcn_permlane32_swap(__float_as_uint(l_reg),__float_as_uint(l_reg),false,false);l_reg=__uint_as_float(rr[0])+__uint_as_float(rr[1]);}
;   if(hi==0)wsf[32+r32]=l_reg;asm volatile("s_waitcnt lgkmcnt(0)":::"memory");
.LBB0_477:
	v_add_f32_e32 v68, v50, v51
	v_add_f32_e32 v68, v52, v68
	v_add_f32_e32 v68, v53, v68
	v_add_f32_e32 v68, v54, v68
	v_add_f32_e32 v68, v55, v68
	v_add_f32_e32 v68, v56, v68
	v_add_f32_e32 v68, v57, v68
	v_add_f32_e32 v68, v58, v68
	v_add_f32_e32 v68, v59, v68
	v_add_f32_e32 v68, v60, v68
	v_add_f32_e32 v68, v61, v68
	v_add_f32_e32 v68, v62, v68
	v_add_f32_e32 v68, v63, v68
	v_add_f32_e32 v68, v64, v68
	v_add_f32_e32 v68, v65, v68
	v_add_f32_e32 v68, v68, v34
	v_add_f32_e32 v68, v35, v68
	v_add_f32_e32 v68, v36, v68
	v_add_f32_e32 v68, v37, v68
	v_add_f32_e32 v68, v38, v68
	v_add_f32_e32 v68, v39, v68
	v_add_f32_e32 v68, v40, v68
	v_add_f32_e32 v68, v41, v68
	v_add_f32_e32 v68, v42, v68
	v_add_f32_e32 v68, v43, v68
	v_add_f32_e32 v68, v44, v68
	s_and_b32 s0, s57, 0x3fffffc0
	v_add_f32_e32 v68, v45, v68
	s_lshl_b32 s0, s0, 2
	v_add_f32_e32 v68, v46, v68
	s_add_i32 s0, s0, 0
	v_add_f32_e32 v68, v47, v68
	s_cmp_lg_u32 0, -1
	v_add_f32_e32 v68, v48, v68
	v_add_f32_e32 v66, v195, v130
	s_cselect_b32 s1, 0, 0
	v_add_f32_e32 v68, v49, v68
	s_addk_i32 s1, 0x6000
	v_add_f32_e32 v66, v66, v68
	v_cvt_pk_bf16_f32 v34, v34, v35
	v_add3_u32 v67, v193, s1, v191
	v_cvt_pk_bf16_f32 v50, v50, v51
	v_cvt_pk_bf16_f32 v51, v52, v53
	v_cvt_pk_bf16_f32 v52, v54, v55
	v_cvt_pk_bf16_f32 v53, v56, v57
	v_cvt_pk_bf16_f32 v54, v58, v59
	v_cvt_pk_bf16_f32 v55, v60, v61
	v_cvt_pk_bf16_f32 v56, v62, v63
	v_cvt_pk_bf16_f32 v57, v64, v65
	v_cvt_pk_bf16_f32 v35, v36, v37
	v_cvt_pk_bf16_f32 v36, v38, v39
	v_cvt_pk_bf16_f32 v37, v40, v41
	v_cvt_pk_bf16_f32 v38, v42, v43
	v_cvt_pk_bf16_f32 v39, v44, v45
	v_cvt_pk_bf16_f32 v40, v46, v47
	v_cvt_pk_bf16_f32 v41, v48, v49
	v_add3_u32 v67, v67, v192, s73
	ds_read_b64_tr_b16 v[42:43],v67 offset:0
	ds_read_b64_tr_b16 v[44:45],v67 offset:512
	ds_read_b64_tr_b16 v[46:47],v67 offset:1024
	ds_read_b64_tr_b16 v[48:49],v67 offset:1536
	ds_read_b64_tr_b16 v[58:59],v67 offset:2048
	ds_read_b64_tr_b16 v[60:61],v67 offset:2560
	ds_read_b64_tr_b16 v[62:63],v67 offset:3072
	ds_read_b64_tr_b16 v[64:65],v67 offset:3584
	s_waitcnt lgkmcnt(0)
	v_mfma_f32_32x32x16_bf16 v[18:33], v[50:53], v[42:45], v[18:33]
	ds_read_b64_tr_b16 v[42:43],v67 offset:4096
	ds_read_b64_tr_b16 v[44:45],v67 offset:4608
	v_mfma_f32_32x32x16_bf16 v[18:33], v[54:57], v[46:49], v[18:33]
	ds_read_b64_tr_b16 v[46:47],v67 offset:5120
	ds_read_b64_tr_b16 v[48:49],v67 offset:5632
	v_mfma_f32_32x32x16_bf16 v[18:33], v[34:37], v[58:61], v[18:33]
	ds_read_b64_tr_b16 v[58:59],v67 offset:6144
	ds_read_b64_tr_b16 v[60:61],v67 offset:6656
	v_mfma_f32_32x32x16_bf16 v[18:33], v[38:41], v[62:65], v[18:33]
	ds_read_b64_tr_b16 v[62:63],v67 offset:7168
	ds_read_b64_tr_b16 v[64:65],v67 offset:7680
	s_waitcnt lgkmcnt(0)
	v_mfma_f32_32x32x16_bf16 v[2:17], v[50:53], v[42:45], v[2:17]
	v_cmp_gt_u32_e32 vcc, 32, v186
	v_mfma_f32_32x32x16_bf16 v[2:17], v[54:57], v[46:49], v[2:17]
	v_mfma_f32_32x32x16_bf16 v[2:17], v[34:37], v[58:61], v[2:17]
	v_mov_b32_e32 v34, v66
	s_nop 1
	v_permlane32_swap_b32_e32 v66, v34
	v_mfma_f32_32x32x16_bf16 v[2:17], v[38:41], v[62:65], v[2:17]
	s_and_saveexec_b64 s[2:3], vcc
	s_cbranch_execz .LBB0_426
	v_add_f32_e32 v34, v66, v34
	v_lshl_add_u32 v35, v187, 2, s0
	ds_write_b32 v35, v34 offset:49280
	s_branch .LBB0_426
